# attention band steps (first step of the band loop body): causal mask regenerated without pads (compares alternate vcc and an SGPR pair) and moved with the row-max tree into the P.V gaps
# speedup vs baseline: 1.0027x; 1.0027x over previous
.LBB0_332:
	v_lshl_add_u64 v[218:219], v[214:215], 0, s[36:37]
	s_mov_b64 s[4:5], 0x4c020000
	s_lshl_b32 s70, s67, 1
	v_lshl_add_u64 v[92:93], v[218:219], 0, s[4:5]
	s_add_i32 s14, s70, s64
	s_mov_b32 s4, m0
	s_mov_b32 m0, s14
	s_nop 0
	global_load_lds_dwordx4 v[92:93], off
	s_mov_b32 m0, s4
	s_mov_b64 s[4:5], 0x4c020080
	v_lshl_add_u64 v[92:93], v[218:219], 0, s[4:5]
	s_add_i32 s4, s14, 0x2000
	s_mov_b32 s5, m0
	s_mov_b32 m0, s4
	s_nop 0
	global_load_lds_dwordx4 v[92:93], off
	s_mov_b32 m0, s5
	s_add_i32 s25, s69, s24
	s_waitcnt lgkmcnt(14)
	v_mfma_f32_32x32x16_bf16 v[32:47], v[164:167], v[208:211], v[32:47]
	v_add_u32_e32 v228, 0xffffffa5, v222
	v_add_u32_e32 v229, 0xffffff85, v222
	v_cmp_le_i32_e32 vcc, v228, v245
	v_cmp_lt_i32_e64 s[98:99], v229, v245
	v_add_u32_e32 v228, 0xffffff85, v222
	v_cndmask_b32_e32 v112, v233, v112, vcc
	v_add_u32_e32 v229, 0xffffffa6, v222
	v_cndmask_b32_e64 v129, v233, v129, s[98:99]
	v_cmp_le_i32_e32 vcc, v228, v245
	v_cmp_le_i32_e64 s[98:99], v229, v245
	v_add_u32_e32 v228, 0xffffff87, v222
	v_cndmask_b32_e32 v128, v233, v128, vcc
	v_add_u32_e32 v229, 0xffffffa7, v222
	v_cndmask_b32_e64 v113, v233, v113, s[98:99]
	v_cmp_le_i32_e32 vcc, v228, v245
	v_cmp_le_i32_e64 s[98:99], v229, v245
	ds_read_b64_tr_b16 v[92:93], v212 offset:32768
	ds_read_b64_tr_b16 v[94:95], v212 offset:33280
	s_waitcnt lgkmcnt(14)
	v_mfma_f32_32x32x16_bf16 v[48:63], v[164:167], v[96:99], v[48:63]
	v_add_u32_e32 v228, 0xffffff88, v222
	v_cndmask_b32_e32 v130, v233, v130, vcc
	v_add_u32_e32 v229, 0xffffffa8, v222
	v_cndmask_b32_e64 v114, v233, v114, s[98:99]
	v_cmp_le_i32_e32 vcc, v228, v245
	v_cmp_le_i32_e64 s[98:99], v229, v245
	v_add_u32_e32 v228, 0xffffff8d, v222
	v_cndmask_b32_e32 v131, v233, v131, vcc
	v_add_u32_e32 v229, 0xffffffad, v222
	v_cndmask_b32_e64 v115, v233, v115, s[98:99]
	v_cmp_le_i32_e32 vcc, v228, v245
	v_cmp_le_i32_e64 s[98:99], v229, v245
	v_add_u32_e32 v228, 0xffffff8e, v222
	v_cndmask_b32_e32 v132, v233, v132, vcc
	v_add_u32_e32 v229, 0xffffffae, v222
	v_cndmask_b32_e64 v116, v233, v116, s[98:99]
	ds_read_b64_tr_b16 v[96:97], v212 offset:36864
	ds_read_b64_tr_b16 v[98:99], v212 offset:37376
	s_waitcnt lgkmcnt(14)
	v_mfma_f32_32x32x16_bf16 v[32:47], v[156:159], v[100:103], v[32:47]
	v_cmp_le_i32_e32 vcc, v228, v245
	v_cmp_le_i32_e64 s[98:99], v229, v245
	v_add_u32_e32 v228, 0xffffff8f, v222
	v_cndmask_b32_e32 v133, v233, v133, vcc
	v_add_u32_e32 v229, 0xffffffaf, v222
	v_cndmask_b32_e64 v117, v233, v117, s[98:99]
	v_cmp_le_i32_e32 vcc, v228, v245
	v_cmp_le_i32_e64 s[98:99], v229, v245
	v_add_u32_e32 v228, 0xffffff90, v222
	v_cndmask_b32_e32 v134, v233, v134, vcc
	v_add_u32_e32 v229, 0xffffffb0, v222
	v_cndmask_b32_e64 v118, v233, v118, s[98:99]
	v_cmp_le_i32_e32 vcc, v228, v245
	v_cmp_le_i32_e64 s[98:99], v229, v245
	v_add_u32_e32 v228, 0xffffff95, v222
	v_cndmask_b32_e32 v135, v233, v135, vcc
	ds_read_b64_tr_b16 v[100:101], v212 offset:33792
	ds_read_b64_tr_b16 v[102:103], v212 offset:34304
	s_waitcnt lgkmcnt(14)
	v_mfma_f32_32x32x16_bf16 v[48:63], v[156:159], v[104:107], v[48:63]
	v_add_u32_e32 v229, 0xffffffb5, v222
	v_cndmask_b32_e64 v119, v233, v119, s[98:99]
	v_cmp_le_i32_e32 vcc, v228, v245
	v_cmp_le_i32_e64 s[98:99], v229, v245
	v_add_u32_e32 v228, 0xffffff96, v222
	v_cndmask_b32_e32 v136, v233, v136, vcc
	v_add_u32_e32 v229, 0xffffffb6, v222
	v_cndmask_b32_e64 v120, v233, v120, s[98:99]
	v_cmp_le_i32_e32 vcc, v228, v245
	v_cmp_le_i32_e64 s[98:99], v229, v245
	v_add_u32_e32 v228, 0xffffff97, v222
	v_cndmask_b32_e32 v137, v233, v137, vcc
	v_add_u32_e32 v229, 0xffffffb7, v222
	v_cndmask_b32_e64 v121, v233, v121, s[98:99]
	v_cmp_le_i32_e32 vcc, v228, v245
	v_cmp_le_i32_e64 s[98:99], v229, v245
	ds_read_b64_tr_b16 v[104:105], v212 offset:37888
	ds_read_b64_tr_b16 v[106:107], v212 offset:38400
	s_waitcnt lgkmcnt(14)
	v_mfma_f32_32x32x16_bf16 v[32:47], v[148:151], v[108:111], v[32:47]
	v_add_u32_e32 v228, 0xffffff98, v222
	v_cndmask_b32_e32 v138, v233, v138, vcc
	v_add_u32_e32 v229, 0xffffffb8, v222
	v_cndmask_b32_e64 v122, v233, v122, s[98:99]
	v_cmp_le_i32_e32 vcc, v228, v245
	v_cmp_le_i32_e64 s[98:99], v229, v245
	v_add_u32_e32 v228, 0xffffff9d, v222
	v_cndmask_b32_e32 v139, v233, v139, vcc
	v_add_u32_e32 v229, 0xffffffbd, v222
	v_cndmask_b32_e64 v123, v233, v123, s[98:99]
	v_cmp_le_i32_e32 vcc, v228, v245
	v_cmp_le_i32_e64 s[98:99], v229, v245
	v_add_u32_e32 v228, 0xffffff9e, v222
	v_cndmask_b32_e32 v140, v233, v140, vcc
	v_add_u32_e32 v229, 0xffffffbe, v222
	v_cndmask_b32_e64 v124, v233, v124, s[98:99]
	ds_read_b64_tr_b16 v[108:109], v212 offset:34816
	ds_read_b64_tr_b16 v[110:111], v212 offset:35328
	s_waitcnt lgkmcnt(14)
	v_mfma_f32_32x32x16_bf16 v[48:63], v[148:151], v[80:83], v[48:63]
	v_cmp_le_i32_e32 vcc, v228, v245
	v_cmp_le_i32_e64 s[98:99], v229, v245
	v_add_u32_e32 v228, 0xffffff9f, v222
	v_cndmask_b32_e32 v141, v233, v141, vcc
	v_add_u32_e32 v229, 0xffffffbf, v222
	v_cndmask_b32_e64 v125, v233, v125, s[98:99]
	v_cmp_le_i32_e32 vcc, v228, v245
	v_cmp_le_i32_e64 s[98:99], v229, v245
	v_add_u32_e32 v228, 0xffffffa0, v222
	v_cndmask_b32_e32 v142, v233, v142, vcc
	v_add_u32_e32 v229, 0xffffffc0, v222
	v_cndmask_b32_e64 v126, v233, v126, s[98:99]
	v_cmp_le_i32_e32 vcc, v228, v245
	v_cmp_le_i32_e64 s[98:99], v229, v245
	s_nop 0
	v_cndmask_b32_e32 v143, v233, v143, vcc
	ds_read_b64_tr_b16 v[80:81], v212 offset:38912
	ds_read_b64_tr_b16 v[82:83], v212 offset:39424
	s_waitcnt lgkmcnt(14)
	v_mfma_f32_32x32x16_bf16 v[32:47], v[144:147], v[84:87], v[32:47]
	v_cndmask_b32_e64 v127, v233, v127, s[98:99]
	v_max_f32_e32 v228, v129, v129
	v_max_f32_e32 v229, v128, v128
	v_max_f32_e32 v228, v229, v228
	v_max3_f32 v229, v130, v131, v113
	v_max3_f32 v228, v228, v112, v114
	v_max3_f32 v228, v228, v115, v132
	v_max3_f32 v229, v229, v134, v135
	v_max3_f32 v228, v228, v133, v116
	v_max3_f32 v229, v229, v118, v119
	v_max3_f32 v228, v228, v117, v136
	v_max3_f32 v229, v229, v138, v139
	v_max3_f32 v228, v228, v137, v120
	v_max3_f32 v229, v229, v122, v123
	v_max3_f32 v228, v228, v121, v140
	v_max3_f32 v229, v229, v142, v143
	ds_read_b64_tr_b16 v[84:85], v212 offset:35840
	ds_read_b64_tr_b16 v[86:87], v212 offset:36352
	s_waitcnt lgkmcnt(14)
	v_mfma_f32_32x32x16_bf16 v[48:63], v[144:147], v[88:91], v[48:63]
	v_max3_f32 v228, v228, v141, v124
	v_max3_f32 v229, v229, v126, v127
	v_max3_f32 v228, v228, v125, v229
	v_mov_b32_e32 v229, v228
	s_nop 1
	v_permlane32_swap_b32_e32 v228, v229
	v_max_f32_e32 v229, v229, v229
	v_max_f32_e32 v228, v228, v228
	v_max_f32_e32 v228, v228, v229
	ds_read_b64_tr_b16 v[88:89], v212 offset:39936
	ds_read_b64_tr_b16 v[90:91], v212 offset:40448
	s_waitcnt lgkmcnt(14)
	v_mfma_f32_32x32x16_bf16 v[16:31], v[164:167], v[92:95], v[16:31]
	v_cmp_lt_f32_e32 vcc, s33, v228
	s_cmp_lg_u64 vcc, 0
	v_add_f32_e32 v223, v249, v176
	s_cselect_b64 s[4:5], -1, 0
	s_cbranch_vccnz .LBB0_372
